# c11 + in-row lane^1/2/4/8 reduction exchanges (wave_sum, final-norm slot sums, row-scale table) as fused v_add_f32_dpp instead of ds_bpermute
# baseline (speedup 1.0000x reference)
; DI unsigned pack_bf16(float lo, float hi) { f32v2 f = {lo, hi}; bf16v2 b = __builtin_convertvector(f, bf16v2); return __builtin_bit_cast(unsigned, b); }
; DI float shx(float v, int o) { int l = (int)__builtin_amdgcn_mbcnt_hi(~0u, __builtin_amdgcn_mbcnt_lo(~0u, 0u)); asm volatile("" : "+v"(l)); return __int_as_float(__builtin_amdgcn_ds_bpermute((l ^ o) << 2, __float_as_int(v))); }
; DI float wave_sum(float v) {
; #pragma unroll
;     for (int o = 32; o >= 1; o >>= 1) v += shx(v, o);
;     return v;
; }
; DI void cvt_phase(const float* __restrict__ x, bf16_t* __restrict__ h, float* __restrict__ ss, int rows) {
;     ...
;         for (int r = 0; r < RB; ++r) {
;             float s2 = 0.f;
; #pragma unroll
;             for (int i = 0; i < 4; ++i) s2 += v[r][i].x * v[r][i].x + v[r][i].y * v[r][i].y + v[r][i].z * v[r][i].z + v[r][i].w * v[r][i].w;
;             s2 = wave_sum(s2);
;             if (lane < 4) *(f32x4*)(ss + (size_t)(row0 + r) * 16 + 4 * lane) = (f32x4){lane == 0 ? s2 : 0.f, 0.f, 0.f, 0.f};
; #pragma unroll
;             for (int i = 0; i < 4; ++i) { uint2 w; w.x = pack_bf16(v[r][i].x, v[r][i].y); w.y = pack_bf16(v[r][i].z, v[r][i].w); *(uint2*)(h + (size_t)(row0 + r) * D + (i * 64 + lane) * 4) = w; }
.LBB0_134:
	s_or_b64 exec, exec, s[4:5]
	s_waitcnt lgkmcnt(0)
	v_lshlrev_b64 v[2:3], 11, v[68:69]
	v_cvt_pk_bf16_f32 v64, v64, v65
	v_cvt_pk_bf16_f32 v65, v66, v67
	v_lshl_add_u64 v[2:3], v[74:75], 0, v[2:3]
	v_cvt_pk_bf16_f32 v60, v60, v61
	v_cvt_pk_bf16_f32 v61, v62, v63
	v_cvt_pk_bf16_f32 v56, v56, v57
	v_cvt_pk_bf16_f32 v57, v58, v59
	v_cvt_pk_bf16_f32 v52, v52, v53
	v_cvt_pk_bf16_f32 v53, v54, v55
	global_store_dwordx2 v[2:3], v[64:65], off
	global_store_dwordx2 v[2:3], v[60:61], off offset:512
	global_store_dwordx2 v[2:3], v[56:57], off offset:1024
	global_store_dwordx2 v[2:3], v[52:53], off offset:1536
	s_waitcnt vmcnt(15)
	v_pk_mul_f32 v[2:3], v[48:49], v[48:49]
	s_waitcnt vmcnt(14)
	v_pk_mul_f32 v[54:55], v[44:45], v[44:45]
	v_pk_mul_f32 v[52:53], v[50:51], v[50:51]
	v_pk_mul_f32 v[56:57], v[46:47], v[46:47]
	v_add_f32_e32 v0, v54, v55
	v_add_f32_e32 v2, v2, v3
	v_add_f32_e32 v0, v0, v56
	v_add_f32_e32 v2, v2, v52
	s_waitcnt vmcnt(13)
	v_pk_mul_f32 v[58:59], v[40:41], v[40:41]
	v_add_f32_e32 v0, v0, v57
	v_add_f32_e32 v2, v2, v53
	v_pk_mul_f32 v[60:61], v[42:43], v[42:43]
	v_add_f32_e32 v0, v2, v0
	v_add_f32_e32 v2, v58, v59
	v_add_f32_e32 v2, v2, v60
	s_waitcnt vmcnt(12)
	v_pk_mul_f32 v[62:63], v[36:37], v[36:37]
	v_add_f32_e32 v2, v2, v61
	v_pk_mul_f32 v[64:65], v[38:39], v[38:39]
	v_add_f32_e32 v0, v0, v2
	v_add_f32_e32 v2, v62, v63
	v_add_f32_e32 v2, v2, v64
	v_add_f32_e32 v2, v2, v65
	v_add_f32_e32 v0, v0, v2
	s_nop 0
	v_mov_b32_e32 v2, v0
	s_nop 1
	v_permlane32_swap_b32_e32 v2, v0
	s_waitcnt lgkmcnt(0)
	v_add_f32_e32 v0, v0, v2
	s_nop 0
	v_mov_b32_e32 v2, v0
	s_nop 1
	v_permlane16_swap_b32_e32 v2, v0
	s_waitcnt lgkmcnt(0)
	v_add_f32_e32 v0, v0, v2
	s_nop 0
	s_waitcnt lgkmcnt(0)
	s_nop 1
	v_add_f32_dpp v0, v0, v0 row_ror:8 row_mask:0xf bank_mask:0xf
	s_nop 0
	s_waitcnt lgkmcnt(0)
	s_nop 1
	v_add_f32_dpp v0, v0, v0 row_ror:4 row_mask:0xf bank_mask:0xf
	s_nop 0
	s_waitcnt lgkmcnt(0)
	s_nop 1
	v_add_f32_dpp v0, v0, v0 quad_perm:[2,3,0,1] row_mask:0xf bank_mask:0xf
	v_mov_b32_e32 v2, v205
	s_nop 0
	v_lshlrev_b32_e32 v2, 2, v2
	v_xor_b32_e32 v2, 4, v2
	ds_bpermute_b32 v2, v2, v0
	s_and_saveexec_b64 s[4:5], vcc
	s_cbranch_execz .LBB0_136
	v_lshlrev_b64 v[52:53], 6, v[80:81]
	s_waitcnt lgkmcnt(0)
	v_add_f32_e32 v0, v0, v2
	v_lshl_add_u64 v[52:53], v[70:71], 0, v[52:53]
	v_cndmask_b32_e64 v0, 0, v0, s[0:1]
	v_mov_b32_e32 v2, v1
	v_mov_b32_e32 v3, v1
	global_store_dwordx4 v[52:53], v[0:3], off
.LBB0_136:
	s_or_b64 exec, exec, s[4:5]
	s_waitcnt lgkmcnt(0)
	v_lshlrev_b64 v[2:3], 11, v[80:81]
	v_cvt_pk_bf16_f32 v48, v48, v49
	v_cvt_pk_bf16_f32 v49, v50, v51
	v_lshl_add_u64 v[2:3], v[74:75], 0, v[2:3]
	v_cvt_pk_bf16_f32 v44, v44, v45
	v_cvt_pk_bf16_f32 v45, v46, v47
	v_cvt_pk_bf16_f32 v40, v40, v41
	v_cvt_pk_bf16_f32 v41, v42, v43
	v_cvt_pk_bf16_f32 v36, v36, v37
	v_cvt_pk_bf16_f32 v37, v38, v39
	global_store_dwordx2 v[2:3], v[48:49], off
	global_store_dwordx2 v[2:3], v[44:45], off offset:512
	global_store_dwordx2 v[2:3], v[40:41], off offset:1024
	global_store_dwordx2 v[2:3], v[36:37], off offset:1536
	s_waitcnt vmcnt(15)
	v_pk_mul_f32 v[2:3], v[32:33], v[32:33]
	s_waitcnt vmcnt(14)
	v_pk_mul_f32 v[38:39], v[28:29], v[28:29]
	v_pk_mul_f32 v[36:37], v[34:35], v[34:35]
	v_pk_mul_f32 v[40:41], v[30:31], v[30:31]
	v_add_f32_e32 v0, v38, v39
	v_add_f32_e32 v2, v2, v3
	v_add_f32_e32 v0, v0, v40
	v_add_f32_e32 v2, v2, v36
	s_waitcnt vmcnt(13)
	v_pk_mul_f32 v[42:43], v[24:25], v[24:25]
	v_add_f32_e32 v0, v0, v41
	v_add_f32_e32 v2, v2, v37
	v_pk_mul_f32 v[44:45], v[26:27], v[26:27]
	v_add_f32_e32 v0, v2, v0
	v_add_f32_e32 v2, v42, v43
	v_add_f32_e32 v2, v2, v44
	s_waitcnt vmcnt(12)
	v_pk_mul_f32 v[46:47], v[20:21], v[20:21]
	v_add_f32_e32 v2, v2, v45
	v_pk_mul_f32 v[48:49], v[22:23], v[22:23]
	v_add_f32_e32 v0, v0, v2
	v_add_f32_e32 v2, v46, v47
	v_add_f32_e32 v2, v2, v48
	v_add_f32_e32 v2, v2, v49
	v_add_f32_e32 v0, v0, v2
	s_nop 0
	v_mov_b32_e32 v2, v0
	s_nop 1
	v_permlane32_swap_b32_e32 v2, v0
	s_waitcnt lgkmcnt(0)
	v_add_f32_e32 v0, v0, v2
	s_nop 0
	v_mov_b32_e32 v2, v0
	s_nop 1
	v_permlane16_swap_b32_e32 v2, v0
	s_waitcnt lgkmcnt(0)
	v_add_f32_e32 v0, v0, v2
	s_nop 0
	s_waitcnt lgkmcnt(0)
	s_nop 1
	v_add_f32_dpp v0, v0, v0 row_ror:8 row_mask:0xf bank_mask:0xf
	s_nop 0
	s_waitcnt lgkmcnt(0)
	s_nop 1
	v_add_f32_dpp v0, v0, v0 row_ror:4 row_mask:0xf bank_mask:0xf
	s_nop 0
	s_waitcnt lgkmcnt(0)
	s_nop 1
	v_add_f32_dpp v0, v0, v0 quad_perm:[2,3,0,1] row_mask:0xf bank_mask:0xf
	v_mov_b32_e32 v2, v205
	s_nop 0
	v_lshlrev_b32_e32 v2, 2, v2
	v_xor_b32_e32 v2, 4, v2
	ds_bpermute_b32 v2, v2, v0
	s_and_saveexec_b64 s[4:5], vcc
	s_cbranch_execz .LBB0_138
	v_lshlrev_b64 v[36:37], 6, v[78:79]
	s_waitcnt lgkmcnt(0)
	v_add_f32_e32 v0, v0, v2
	v_lshl_add_u64 v[36:37], v[70:71], 0, v[36:37]
	v_cndmask_b32_e64 v0, 0, v0, s[0:1]
	v_mov_b32_e32 v2, v1
	v_mov_b32_e32 v3, v1
	global_store_dwordx4 v[36:37], v[0:3], off
; DI unsigned pack_bf16(float lo, float hi) { f32v2 f = {lo, hi}; bf16v2 b = __builtin_convertvector(f, bf16v2); return __builtin_bit_cast(unsigned, b); }
; DI float shx(float v, int o) { int l = (int)__builtin_amdgcn_mbcnt_hi(~0u, __builtin_amdgcn_mbcnt_lo(~0u, 0u)); asm volatile("" : "+v"(l)); return __int_as_float(__builtin_amdgcn_ds_bpermute((l ^ o) << 2, __float_as_int(v))); }
; DI float wave_sum(float v) {
; #pragma unroll
;     for (int o = 32; o >= 1; o >>= 1) v += shx(v, o);
;     return v;
; }
; DI void cvt_phase(const float* __restrict__ x, bf16_t* __restrict__ h, float* __restrict__ ss, int rows) {
;     ...
;         for (int r = 0; r < RB; ++r) {
;             float s2 = 0.f;
; #pragma unroll
;             for (int i = 0; i < 4; ++i) s2 += v[r][i].x * v[r][i].x + v[r][i].y * v[r][i].y + v[r][i].z * v[r][i].z + v[r][i].w * v[r][i].w;
;             s2 = wave_sum(s2);
;             if (lane < 4) *(f32x4*)(ss + (size_t)(row0 + r) * 16 + 4 * lane) = (f32x4){lane == 0 ? s2 : 0.f, 0.f, 0.f, 0.f};
; #pragma unroll
;             for (int i = 0; i < 4; ++i) { uint2 w; w.x = pack_bf16(v[r][i].x, v[r][i].y); w.y = pack_bf16(v[r][i].z, v[r][i].w); *(uint2*)(h + (size_t)(row0 + r) * D + (i * 64 + lane) * 4) = w; }
.LBB0_138:
	s_or_b64 exec, exec, s[4:5]
	s_waitcnt lgkmcnt(0)
	v_lshlrev_b64 v[2:3], 11, v[78:79]
	v_cvt_pk_bf16_f32 v32, v32, v33
	v_cvt_pk_bf16_f32 v33, v34, v35
	v_lshl_add_u64 v[2:3], v[74:75], 0, v[2:3]
	v_cvt_pk_bf16_f32 v28, v28, v29
	v_cvt_pk_bf16_f32 v29, v30, v31
	v_cvt_pk_bf16_f32 v24, v24, v25
	v_cvt_pk_bf16_f32 v25, v26, v27
	v_cvt_pk_bf16_f32 v20, v20, v21
	v_cvt_pk_bf16_f32 v21, v22, v23
	global_store_dwordx2 v[2:3], v[32:33], off
	global_store_dwordx2 v[2:3], v[28:29], off offset:512
	global_store_dwordx2 v[2:3], v[24:25], off offset:1024
	global_store_dwordx2 v[2:3], v[20:21], off offset:1536
	s_waitcnt vmcnt(15)
	v_pk_mul_f32 v[2:3], v[16:17], v[16:17]
	s_waitcnt vmcnt(14)
	v_pk_mul_f32 v[22:23], v[12:13], v[12:13]
	v_pk_mul_f32 v[20:21], v[18:19], v[18:19]
	v_pk_mul_f32 v[24:25], v[14:15], v[14:15]
	v_add_f32_e32 v0, v22, v23
	v_add_f32_e32 v2, v2, v3
	v_add_f32_e32 v0, v0, v24
	v_add_f32_e32 v2, v2, v20
	s_waitcnt vmcnt(13)
	v_pk_mul_f32 v[26:27], v[8:9], v[8:9]
	v_add_f32_e32 v0, v0, v25
	v_add_f32_e32 v2, v2, v21
	v_pk_mul_f32 v[28:29], v[10:11], v[10:11]
	v_add_f32_e32 v0, v2, v0
	v_add_f32_e32 v2, v26, v27
	v_add_f32_e32 v2, v2, v28
	s_waitcnt vmcnt(12)
	v_pk_mul_f32 v[30:31], v[4:5], v[4:5]
	v_add_f32_e32 v2, v2, v29
	v_pk_mul_f32 v[32:33], v[6:7], v[6:7]
	v_add_f32_e32 v0, v0, v2
	v_add_f32_e32 v2, v30, v31
	v_add_f32_e32 v2, v2, v32
	v_add_f32_e32 v2, v2, v33
	v_add_f32_e32 v0, v0, v2
	s_nop 0
	v_mov_b32_e32 v2, v0
	s_nop 1
	v_permlane32_swap_b32_e32 v2, v0
	s_waitcnt lgkmcnt(0)
	v_add_f32_e32 v0, v0, v2
	s_nop 0
	v_mov_b32_e32 v2, v0
	s_nop 1
	v_permlane16_swap_b32_e32 v2, v0
	s_waitcnt lgkmcnt(0)
	v_add_f32_e32 v0, v0, v2
	s_nop 0
	s_waitcnt lgkmcnt(0)
	s_nop 1
	v_add_f32_dpp v0, v0, v0 row_ror:8 row_mask:0xf bank_mask:0xf
	s_nop 0
	s_waitcnt lgkmcnt(0)
	s_nop 1
	v_add_f32_dpp v0, v0, v0 row_ror:4 row_mask:0xf bank_mask:0xf
	s_nop 0
	s_waitcnt lgkmcnt(0)
	s_nop 1
	v_add_f32_dpp v0, v0, v0 quad_perm:[2,3,0,1] row_mask:0xf bank_mask:0xf
	v_mov_b32_e32 v2, v205
	s_nop 0
	v_lshlrev_b32_e32 v2, 2, v2
	v_xor_b32_e32 v2, 4, v2
	ds_bpermute_b32 v2, v2, v0
	s_and_saveexec_b64 s[4:5], vcc
	s_cbranch_execz .LBB0_131
	v_lshlrev_b64 v[20:21], 6, v[76:77]
	s_waitcnt lgkmcnt(0)
	v_add_f32_e32 v0, v0, v2
	v_lshl_add_u64 v[20:21], v[70:71], 0, v[20:21]
	v_cndmask_b32_e64 v0, 0, v0, s[0:1]
	v_mov_b32_e32 v2, v1
	v_mov_b32_e32 v3, v1
	global_store_dwordx4 v[20:21], v[0:3], off
	s_branch .LBB0_131

; DI float shx(float v, int o) { int l = (int)__builtin_amdgcn_mbcnt_hi(~0u, __builtin_amdgcn_mbcnt_lo(~0u, 0u)); asm volatile("" : "+v"(l)); return __int_as_float(__builtin_amdgcn_ds_bpermute((l ^ o) << 2, __float_as_int(v))); }
; DI void final_norm_phase(const bf16_t* __restrict__ h, const float* __restrict__ ss, float* __restrict__ out, const float* __restrict__ g, int rows) {
;     ...
;     for (int row0 = (blockIdx.x * 8 + wave) * RB; row0 < rows; row0 += gridDim.x * 8 * RB) {
;         u32x4 v[RB][2]; float sp[RB];
; #pragma unroll
;         for (int r = 0; r < RB; ++r) {
;             const bf16_t* hp = h + (size_t)(row0 + r) * D + lane * 16;
;             v[r][0] = *(const u32x4*)hp; v[r][1] = *(const u32x4*)(hp + 8);
;             sp[r] = ss[(size_t)(row0 + r) * 16 + (lane & 15)];
;         }
; #pragma unroll
;         for (int r = 0; r < RB; ++r) {
;             float s = sp[r]; s += shx(s, 1); s += shx(s, 2); s += shx(s, 4); s += shx(s, 8);
;             const float rstd = rsqrtf(s * (1.0f / D) + 1e-6f);
;             float f[16]; unpack8(v[r][0], f); unpack8(v[r][1], f + 8);
;             float* op = out + (size_t)(row0 + r) * D + lane * 16;
; #pragma unroll
;             for (int i = 0; i < 4; ++i) { float4 o; o.x = f[4 * i] * rstd * gg[4 * i]; o.y = f[4 * i + 1] * rstd * gg[4 * i + 1]; o.z = f[4 * i + 2] * rstd * gg[4 * i + 2]; o.w = f[4 * i + 3] * rstd * gg[4 * i + 3]; ((float4*)op)[i] = o; }
;         }
.LBB0_1388:
	v_ashrrev_i32_e32 v83, 31, v82
	v_lshlrev_b64 v[18:19], 11, v[82:83]
	v_lshl_add_u64 v[18:19], v[84:85], 0, v[18:19]
	global_load_dwordx4 v[74:77], v[18:19], off offset:16
	global_load_dwordx4 v[78:81], v[18:19], off
	v_lshlrev_b64 v[18:19], 6, v[82:83]
	v_lshl_add_u64 v[18:19], v[86:87], 0, v[18:19]
	global_load_dword v0, v[18:19], off
	v_add_u32_e32 v102, 1, v82
	v_ashrrev_i32_e32 v103, 31, v102
	v_lshlrev_b64 v[18:19], 11, v[102:103]
	v_lshl_add_u64 v[18:19], v[84:85], 0, v[18:19]
	global_load_dwordx4 v[66:69], v[18:19], off offset:16
	global_load_dwordx4 v[70:73], v[18:19], off
	v_lshlrev_b64 v[18:19], 6, v[102:103]
	v_lshl_add_u64 v[18:19], v[86:87], 0, v[18:19]
	v_add_u32_e32 v100, 2, v82
	global_load_dword v110, v[18:19], off
	v_ashrrev_i32_e32 v101, 31, v100
	v_lshlrev_b64 v[18:19], 11, v[100:101]
	v_lshl_add_u64 v[18:19], v[84:85], 0, v[18:19]
	global_load_dwordx4 v[58:61], v[18:19], off offset:16
	global_load_dwordx4 v[62:65], v[18:19], off
	v_lshlrev_b64 v[18:19], 6, v[100:101]
	v_add_u32_e32 v98, 3, v82
	v_lshl_add_u64 v[18:19], v[86:87], 0, v[18:19]
	v_ashrrev_i32_e32 v99, 31, v98
	global_load_dword v109, v[18:19], off
	v_lshlrev_b64 v[18:19], 11, v[98:99]
	v_lshl_add_u64 v[18:19], v[84:85], 0, v[18:19]
	global_load_dwordx4 v[50:53], v[18:19], off offset:16
	global_load_dwordx4 v[54:57], v[18:19], off
	v_lshlrev_b64 v[18:19], 6, v[98:99]
	v_add_u32_e32 v96, 4, v82
	v_lshl_add_u64 v[18:19], v[86:87], 0, v[18:19]
	v_ashrrev_i32_e32 v97, 31, v96
	global_load_dword v108, v[18:19], off
	v_lshlrev_b64 v[18:19], 11, v[96:97]
	v_lshl_add_u64 v[18:19], v[84:85], 0, v[18:19]
	global_load_dwordx4 v[42:45], v[18:19], off offset:16
	global_load_dwordx4 v[46:49], v[18:19], off
	v_lshlrev_b64 v[18:19], 6, v[96:97]
	v_add_u32_e32 v94, 5, v82
	v_lshl_add_u64 v[18:19], v[86:87], 0, v[18:19]
	v_ashrrev_i32_e32 v95, 31, v94
	global_load_dword v107, v[18:19], off
	v_lshlrev_b64 v[18:19], 11, v[94:95]
	v_lshl_add_u64 v[18:19], v[84:85], 0, v[18:19]
	global_load_dwordx4 v[34:37], v[18:19], off offset:16
	global_load_dwordx4 v[38:41], v[18:19], off
	v_lshlrev_b64 v[18:19], 6, v[94:95]
	v_add_u32_e32 v92, 6, v82
	v_lshl_add_u64 v[18:19], v[86:87], 0, v[18:19]
	v_ashrrev_i32_e32 v93, 31, v92
	global_load_dword v106, v[18:19], off
	v_lshlrev_b64 v[18:19], 11, v[92:93]
	v_lshl_add_u64 v[18:19], v[84:85], 0, v[18:19]
	global_load_dwordx4 v[26:29], v[18:19], off offset:16
	global_load_dwordx4 v[30:33], v[18:19], off
	v_lshlrev_b64 v[18:19], 6, v[92:93]
	v_add_u32_e32 v90, 7, v82
	v_lshl_add_u64 v[18:19], v[86:87], 0, v[18:19]
	v_ashrrev_i32_e32 v91, 31, v90
	global_load_dword v105, v[18:19], off
	v_lshlrev_b64 v[18:19], 11, v[90:91]
	v_lshlrev_b64 v[112:113], 6, v[90:91]
	v_lshl_add_u64 v[22:23], v[84:85], 0, v[18:19]
	v_lshl_add_u64 v[112:113], v[86:87], 0, v[112:113]
	global_load_dwordx4 v[18:21], v[22:23], off offset:16
	s_nop 0
	global_load_dwordx4 v[22:25], v[22:23], off
	s_nop 0
	global_load_dword v104, v[112:113], off
	v_lshlrev_b64 v[112:113], 12, v[82:83]
	v_lshl_add_u64 v[116:117], v[88:89], 0, v[112:113]
	v_add_u32_e32 v82, s35, v82
	s_waitcnt vmcnt(22)
	v_lshlrev_b32_e32 v112, 16, v78
	v_and_b32_e32 v113, 0xffff0000, v78
	v_lshlrev_b32_e32 v78, 16, v79
	s_waitcnt vmcnt(21)
	v_and_b32_e32 v79, 0xffff0000, v79
	s_waitcnt lgkmcnt(0)
	s_nop 1
	v_add_f32_dpp v0, v0, v0 quad_perm:[1,0,3,2] row_mask:0xf bank_mask:0xf
	s_nop 0
	s_waitcnt lgkmcnt(0)
	s_nop 1
	v_add_f32_dpp v0, v0, v0 quad_perm:[2,3,0,1] row_mask:0xf bank_mask:0xf
	s_nop 0
	s_waitcnt lgkmcnt(0)
	s_nop 1
	v_add_f32_dpp v0, v0, v0 row_ror:4 row_mask:0xf bank_mask:0xf
	s_nop 0
	s_waitcnt lgkmcnt(0)
	s_nop 1
	v_add_f32_dpp v0, v0, v0 row_ror:8 row_mask:0xf bank_mask:0xf
	v_fmamk_f32 v0, v0, 0x3a800000, v194
	v_cmp_gt_f32_e32 vcc, s49, v0
	v_mul_f32_e32 v111, 0x4b800000, v0
	s_nop 0
	v_cndmask_b32_e32 v0, v0, v111, vcc
	v_rsq_f32_e32 v0, v0
	s_nop 0
	v_mul_f32_e32 v111, 0x45800000, v0
	v_cndmask_b32_e32 v0, v0, v111, vcc
	v_pk_mul_f32 v[78:79], v[0:1], v[78:79] op_sel_hi:[0,1]
	v_pk_mul_f32 v[114:115], v[16:17], v[78:79]
	v_lshlrev_b32_e32 v78, 16, v80
	v_and_b32_e32 v79, 0xffff0000, v80
	v_lshlrev_b32_e32 v80, 16, v81
	v_and_b32_e32 v81, 0xffff0000, v81
	v_pk_mul_f32 v[78:79], v[0:1], v[78:79] op_sel_hi:[0,1]
	v_pk_mul_f32 v[80:81], v[0:1], v[80:81] op_sel_hi:[0,1]
	v_pk_mul_f32 v[78:79], v[10:11], v[78:79]
	v_pk_mul_f32 v[80:81], v[12:13], v[80:81]
	global_store_dwordx4 v[116:117], v[78:81], off offset:16
	v_pk_mul_f32 v[112:113], v[0:1], v[112:113] op_sel_hi:[0,1]
	v_pk_mul_f32 v[112:113], v[14:15], v[112:113]
	v_lshlrev_b32_e32 v78, 16, v74
	v_and_b32_e32 v79, 0xffff0000, v74
	v_lshlrev_b32_e32 v74, 16, v75
	v_and_b32_e32 v75, 0xffff0000, v75
	v_pk_mul_f32 v[74:75], v[0:1], v[74:75] op_sel_hi:[0,1]
	v_pk_mul_f32 v[80:81], v[8:9], v[74:75]
	v_lshlrev_b32_e32 v74, 16, v76
	v_and_b32_e32 v75, 0xffff0000, v76
	v_lshlrev_b32_e32 v76, 16, v77
	v_and_b32_e32 v77, 0xffff0000, v77
	v_pk_mul_f32 v[78:79], v[0:1], v[78:79] op_sel_hi:[0,1]
	v_pk_mul_f32 v[74:75], v[0:1], v[74:75] op_sel_hi:[0,1]
	v_pk_mul_f32 v[76:77], v[0:1], v[76:77] op_sel_hi:[0,1]
	v_pk_mul_f32 v[78:79], v[6:7], v[78:79]
	v_pk_mul_f32 v[74:75], v[2:3], v[74:75]
	v_pk_mul_f32 v[76:77], v[4:5], v[76:77]
	global_store_dwordx4 v[116:117], v[112:115], off
	global_store_dwordx4 v[116:117], v[78:81], off offset:32
	global_store_dwordx4 v[116:117], v[74:77], off offset:48
	s_nop 0
	s_waitcnt vmcnt(22)
	s_waitcnt lgkmcnt(0)
	s_nop 1
	v_add_f32_dpp v0, v110, v110 quad_perm:[1,0,3,2] row_mask:0xf bank_mask:0xf
	s_waitcnt lgkmcnt(0)
	s_nop 1
	v_add_f32_dpp v0, v0, v0 quad_perm:[2,3,0,1] row_mask:0xf bank_mask:0xf
	s_nop 0
	s_waitcnt lgkmcnt(0)
; DI float shx(float v, int o) { int l = (int)__builtin_amdgcn_mbcnt_hi(~0u, __builtin_amdgcn_mbcnt_lo(~0u, 0u)); asm volatile("" : "+v"(l)); return __int_as_float(__builtin_amdgcn_ds_bpermute((l ^ o) << 2, __float_as_int(v))); }
; DI void final_norm_phase(const bf16_t* __restrict__ h, const float* __restrict__ ss, float* __restrict__ out, const float* __restrict__ g, int rows) {
;     ...
;     for (int row0 = (blockIdx.x * 8 + wave) * RB; row0 < rows; row0 += gridDim.x * 8 * RB) {
;         u32x4 v[RB][2]; float sp[RB];
; #pragma unroll
;         for (int r = 0; r < RB; ++r) {
;             const bf16_t* hp = h + (size_t)(row0 + r) * D + lane * 16;
;             v[r][0] = *(const u32x4*)hp; v[r][1] = *(const u32x4*)(hp + 8);
;             sp[r] = ss[(size_t)(row0 + r) * 16 + (lane & 15)];
;         }
; #pragma unroll
;         for (int r = 0; r < RB; ++r) {
;             float s = sp[r]; s += shx(s, 1); s += shx(s, 2); s += shx(s, 4); s += shx(s, 8);
;             const float rstd = rsqrtf(s * (1.0f / D) + 1e-6f);
;             float f[16]; unpack8(v[r][0], f); unpack8(v[r][1], f + 8);
;             float* op = out + (size_t)(row0 + r) * D + lane * 16;
; #pragma unroll
;             for (int i = 0; i < 4; ++i) { float4 o; o.x = f[4 * i] * rstd * gg[4 * i]; o.y = f[4 * i + 1] * rstd * gg[4 * i + 1]; o.z = f[4 * i + 2] * rstd * gg[4 * i + 2]; o.w = f[4 * i + 3] * rstd * gg[4 * i + 3]; ((float4*)op)[i] = o; }
;         }
	s_nop 1
	v_add_f32_dpp v0, v0, v0 row_ror:4 row_mask:0xf bank_mask:0xf
	s_nop 0
	s_waitcnt lgkmcnt(0)
	s_nop 1
	v_add_f32_dpp v0, v0, v0 row_ror:8 row_mask:0xf bank_mask:0xf
	v_fmamk_f32 v0, v0, 0x3a800000, v194
	v_cmp_gt_f32_e32 vcc, s49, v0
	v_mul_f32_e32 v74, 0x4b800000, v0
	s_nop 0
	v_cndmask_b32_e32 v0, v0, v74, vcc
	v_rsq_f32_e32 v0, v0
	s_nop 0
	v_mul_f32_e32 v74, 0x45800000, v0
	v_cndmask_b32_e32 v0, v0, v74, vcc
	v_lshlrev_b64 v[74:75], 12, v[102:103]
	v_lshl_add_u64 v[78:79], v[88:89], 0, v[74:75]
	v_lshlrev_b32_e32 v74, 16, v70
	v_and_b32_e32 v75, 0xffff0000, v70
	v_lshlrev_b32_e32 v70, 16, v71
	v_and_b32_e32 v71, 0xffff0000, v71
	v_pk_mul_f32 v[70:71], v[0:1], v[70:71] op_sel_hi:[0,1]
	v_pk_mul_f32 v[76:77], v[16:17], v[70:71]
	v_lshlrev_b32_e32 v70, 16, v72
	v_and_b32_e32 v71, 0xffff0000, v72
	v_lshlrev_b32_e32 v72, 16, v73
	v_and_b32_e32 v73, 0xffff0000, v73
	v_pk_mul_f32 v[70:71], v[0:1], v[70:71] op_sel_hi:[0,1]
	v_pk_mul_f32 v[72:73], v[0:1], v[72:73] op_sel_hi:[0,1]
	v_pk_mul_f32 v[70:71], v[10:11], v[70:71]
	v_pk_mul_f32 v[72:73], v[12:13], v[72:73]
	global_store_dwordx4 v[78:79], v[70:73], off offset:16
	v_pk_mul_f32 v[74:75], v[0:1], v[74:75] op_sel_hi:[0,1]
	v_pk_mul_f32 v[74:75], v[14:15], v[74:75]
	v_lshlrev_b32_e32 v70, 16, v66
	v_and_b32_e32 v71, 0xffff0000, v66
	v_lshlrev_b32_e32 v66, 16, v67
	v_and_b32_e32 v67, 0xffff0000, v67
	v_pk_mul_f32 v[66:67], v[0:1], v[66:67] op_sel_hi:[0,1]
	v_pk_mul_f32 v[72:73], v[8:9], v[66:67]
	v_lshlrev_b32_e32 v66, 16, v68
	v_and_b32_e32 v67, 0xffff0000, v68
	v_lshlrev_b32_e32 v68, 16, v69
	v_and_b32_e32 v69, 0xffff0000, v69
	v_pk_mul_f32 v[70:71], v[0:1], v[70:71] op_sel_hi:[0,1]
	v_pk_mul_f32 v[66:67], v[0:1], v[66:67] op_sel_hi:[0,1]
	v_pk_mul_f32 v[68:69], v[0:1], v[68:69] op_sel_hi:[0,1]
	v_pk_mul_f32 v[70:71], v[6:7], v[70:71]
	v_pk_mul_f32 v[66:67], v[2:3], v[66:67]
	v_pk_mul_f32 v[68:69], v[4:5], v[68:69]
	global_store_dwordx4 v[78:79], v[74:77], off
	global_store_dwordx4 v[78:79], v[70:73], off offset:32
	global_store_dwordx4 v[78:79], v[66:69], off offset:48
	s_nop 0
	s_waitcnt vmcnt(23)
	s_waitcnt lgkmcnt(0)
	s_nop 1
	v_add_f32_dpp v0, v109, v109 quad_perm:[1,0,3,2] row_mask:0xf bank_mask:0xf
	s_waitcnt lgkmcnt(0)
	s_nop 1
	v_add_f32_dpp v0, v0, v0 quad_perm:[2,3,0,1] row_mask:0xf bank_mask:0xf
	s_nop 0
	s_waitcnt lgkmcnt(0)
	s_nop 1
	v_add_f32_dpp v0, v0, v0 row_ror:4 row_mask:0xf bank_mask:0xf
	s_nop 0
	s_waitcnt lgkmcnt(0)
	s_nop 1
	v_add_f32_dpp v0, v0, v0 row_ror:8 row_mask:0xf bank_mask:0xf
	v_fmamk_f32 v0, v0, 0x3a800000, v194
	v_cmp_gt_f32_e32 vcc, s49, v0
	v_mul_f32_e32 v66, 0x4b800000, v0
	s_nop 0
	v_cndmask_b32_e32 v0, v0, v66, vcc
	v_rsq_f32_e32 v0, v0
	s_nop 0
	v_mul_f32_e32 v66, 0x45800000, v0
	v_cndmask_b32_e32 v0, v0, v66, vcc
	v_lshlrev_b64 v[66:67], 12, v[100:101]
	v_lshl_add_u64 v[70:71], v[88:89], 0, v[66:67]
	v_lshlrev_b32_e32 v66, 16, v62
	v_and_b32_e32 v67, 0xffff0000, v62
	v_lshlrev_b32_e32 v62, 16, v63
	v_and_b32_e32 v63, 0xffff0000, v63
	v_pk_mul_f32 v[62:63], v[0:1], v[62:63] op_sel_hi:[0,1]
	v_pk_mul_f32 v[68:69], v[16:17], v[62:63]
	v_lshlrev_b32_e32 v62, 16, v64
	v_and_b32_e32 v63, 0xffff0000, v64
	v_lshlrev_b32_e32 v64, 16, v65
	v_and_b32_e32 v65, 0xffff0000, v65
	v_pk_mul_f32 v[62:63], v[0:1], v[62:63] op_sel_hi:[0,1]
	v_pk_mul_f32 v[64:65], v[0:1], v[64:65] op_sel_hi:[0,1]
	v_pk_mul_f32 v[62:63], v[10:11], v[62:63]
	v_pk_mul_f32 v[64:65], v[12:13], v[64:65]
	global_store_dwordx4 v[70:71], v[62:65], off offset:16
	v_pk_mul_f32 v[66:67], v[0:1], v[66:67] op_sel_hi:[0,1]
	v_pk_mul_f32 v[66:67], v[14:15], v[66:67]
	v_lshlrev_b32_e32 v62, 16, v58
	v_and_b32_e32 v63, 0xffff0000, v58
	v_lshlrev_b32_e32 v58, 16, v59
	v_and_b32_e32 v59, 0xffff0000, v59
	v_pk_mul_f32 v[58:59], v[0:1], v[58:59] op_sel_hi:[0,1]
	v_pk_mul_f32 v[64:65], v[8:9], v[58:59]
	v_lshlrev_b32_e32 v58, 16, v60
	v_and_b32_e32 v59, 0xffff0000, v60
	v_lshlrev_b32_e32 v60, 16, v61
	v_and_b32_e32 v61, 0xffff0000, v61
	v_pk_mul_f32 v[62:63], v[0:1], v[62:63] op_sel_hi:[0,1]
	v_pk_mul_f32 v[58:59], v[0:1], v[58:59] op_sel_hi:[0,1]
	v_pk_mul_f32 v[60:61], v[0:1], v[60:61] op_sel_hi:[0,1]
	v_pk_mul_f32 v[62:63], v[6:7], v[62:63]
	v_pk_mul_f32 v[58:59], v[2:3], v[58:59]
	v_pk_mul_f32 v[60:61], v[4:5], v[60:61]
	global_store_dwordx4 v[70:71], v[66:69], off
	global_store_dwordx4 v[70:71], v[62:65], off offset:32
	global_store_dwordx4 v[70:71], v[58:61], off offset:48
	s_nop 0
	s_waitcnt vmcnt(24)
	s_waitcnt lgkmcnt(0)
	s_nop 1
	v_add_f32_dpp v0, v108, v108 quad_perm:[1,0,3,2] row_mask:0xf bank_mask:0xf
	s_waitcnt lgkmcnt(0)
	s_nop 1
	v_add_f32_dpp v0, v0, v0 quad_perm:[2,3,0,1] row_mask:0xf bank_mask:0xf
	s_nop 0
	s_waitcnt lgkmcnt(0)
	s_nop 1
	v_add_f32_dpp v0, v0, v0 row_ror:4 row_mask:0xf bank_mask:0xf
	s_nop 0
	s_waitcnt lgkmcnt(0)
; DI float shx(float v, int o) { int l = (int)__builtin_amdgcn_mbcnt_hi(~0u, __builtin_amdgcn_mbcnt_lo(~0u, 0u)); asm volatile("" : "+v"(l)); return __int_as_float(__builtin_amdgcn_ds_bpermute((l ^ o) << 2, __float_as_int(v))); }
; DI void final_norm_phase(const bf16_t* __restrict__ h, const float* __restrict__ ss, float* __restrict__ out, const float* __restrict__ g, int rows) {
;     ...
;     for (int row0 = (blockIdx.x * 8 + wave) * RB; row0 < rows; row0 += gridDim.x * 8 * RB) {
;         u32x4 v[RB][2]; float sp[RB];
; #pragma unroll
;         for (int r = 0; r < RB; ++r) {
;             const bf16_t* hp = h + (size_t)(row0 + r) * D + lane * 16;
;             v[r][0] = *(const u32x4*)hp; v[r][1] = *(const u32x4*)(hp + 8);
;             sp[r] = ss[(size_t)(row0 + r) * 16 + (lane & 15)];
;         }
; #pragma unroll
;         for (int r = 0; r < RB; ++r) {
;             float s = sp[r]; s += shx(s, 1); s += shx(s, 2); s += shx(s, 4); s += shx(s, 8);
;             const float rstd = rsqrtf(s * (1.0f / D) + 1e-6f);
;             float f[16]; unpack8(v[r][0], f); unpack8(v[r][1], f + 8);
;             float* op = out + (size_t)(row0 + r) * D + lane * 16;
; #pragma unroll
;             for (int i = 0; i < 4; ++i) { float4 o; o.x = f[4 * i] * rstd * gg[4 * i]; o.y = f[4 * i + 1] * rstd * gg[4 * i + 1]; o.z = f[4 * i + 2] * rstd * gg[4 * i + 2]; o.w = f[4 * i + 3] * rstd * gg[4 * i + 3]; ((float4*)op)[i] = o; }
;         }
	s_nop 1
	v_add_f32_dpp v0, v0, v0 row_ror:8 row_mask:0xf bank_mask:0xf
	v_fmamk_f32 v0, v0, 0x3a800000, v194
	v_cmp_gt_f32_e32 vcc, s49, v0
	v_mul_f32_e32 v58, 0x4b800000, v0
	s_nop 0
	v_cndmask_b32_e32 v0, v0, v58, vcc
	v_rsq_f32_e32 v0, v0
	s_nop 0
	v_mul_f32_e32 v58, 0x45800000, v0
	v_cndmask_b32_e32 v0, v0, v58, vcc
	v_lshlrev_b64 v[58:59], 12, v[98:99]
	v_lshl_add_u64 v[62:63], v[88:89], 0, v[58:59]
	v_lshlrev_b32_e32 v58, 16, v54
	v_and_b32_e32 v59, 0xffff0000, v54
	v_lshlrev_b32_e32 v54, 16, v55
	v_and_b32_e32 v55, 0xffff0000, v55
	v_pk_mul_f32 v[54:55], v[0:1], v[54:55] op_sel_hi:[0,1]
	v_pk_mul_f32 v[60:61], v[16:17], v[54:55]
	v_lshlrev_b32_e32 v54, 16, v56
	v_and_b32_e32 v55, 0xffff0000, v56
	v_lshlrev_b32_e32 v56, 16, v57
	v_and_b32_e32 v57, 0xffff0000, v57
	v_pk_mul_f32 v[54:55], v[0:1], v[54:55] op_sel_hi:[0,1]
	v_pk_mul_f32 v[56:57], v[0:1], v[56:57] op_sel_hi:[0,1]
	v_pk_mul_f32 v[54:55], v[10:11], v[54:55]
	v_pk_mul_f32 v[56:57], v[12:13], v[56:57]
	global_store_dwordx4 v[62:63], v[54:57], off offset:16
	v_pk_mul_f32 v[58:59], v[0:1], v[58:59] op_sel_hi:[0,1]
	v_pk_mul_f32 v[58:59], v[14:15], v[58:59]
	v_lshlrev_b32_e32 v54, 16, v50
	v_and_b32_e32 v55, 0xffff0000, v50
	v_lshlrev_b32_e32 v50, 16, v51
	v_and_b32_e32 v51, 0xffff0000, v51
	v_pk_mul_f32 v[50:51], v[0:1], v[50:51] op_sel_hi:[0,1]
	v_pk_mul_f32 v[56:57], v[8:9], v[50:51]
	v_lshlrev_b32_e32 v50, 16, v52
	v_and_b32_e32 v51, 0xffff0000, v52
	v_lshlrev_b32_e32 v52, 16, v53
	v_and_b32_e32 v53, 0xffff0000, v53
	v_pk_mul_f32 v[54:55], v[0:1], v[54:55] op_sel_hi:[0,1]
	v_pk_mul_f32 v[50:51], v[0:1], v[50:51] op_sel_hi:[0,1]
	v_pk_mul_f32 v[52:53], v[0:1], v[52:53] op_sel_hi:[0,1]
	v_pk_mul_f32 v[54:55], v[6:7], v[54:55]
	v_pk_mul_f32 v[50:51], v[2:3], v[50:51]
	v_pk_mul_f32 v[52:53], v[4:5], v[52:53]
	global_store_dwordx4 v[62:63], v[58:61], off
	global_store_dwordx4 v[62:63], v[54:57], off offset:32
	global_store_dwordx4 v[62:63], v[50:53], off offset:48
	s_nop 0
	s_waitcnt vmcnt(25)
	s_waitcnt lgkmcnt(0)
	s_nop 1
	v_add_f32_dpp v0, v107, v107 quad_perm:[1,0,3,2] row_mask:0xf bank_mask:0xf
	s_waitcnt lgkmcnt(0)
	s_nop 1
	v_add_f32_dpp v0, v0, v0 quad_perm:[2,3,0,1] row_mask:0xf bank_mask:0xf
	s_nop 0
	s_waitcnt lgkmcnt(0)
	s_nop 1
	v_add_f32_dpp v0, v0, v0 row_ror:4 row_mask:0xf bank_mask:0xf
	s_nop 0
	s_waitcnt lgkmcnt(0)
	s_nop 1
	v_add_f32_dpp v0, v0, v0 row_ror:8 row_mask:0xf bank_mask:0xf
	v_fmamk_f32 v0, v0, 0x3a800000, v194
	v_cmp_gt_f32_e32 vcc, s49, v0
	v_mul_f32_e32 v50, 0x4b800000, v0
	s_nop 0
	v_cndmask_b32_e32 v0, v0, v50, vcc
	v_rsq_f32_e32 v0, v0
	s_nop 0
	v_mul_f32_e32 v50, 0x45800000, v0
	v_cndmask_b32_e32 v0, v0, v50, vcc
	v_lshlrev_b64 v[50:51], 12, v[96:97]
	v_lshl_add_u64 v[54:55], v[88:89], 0, v[50:51]
	v_lshlrev_b32_e32 v50, 16, v46
	v_and_b32_e32 v51, 0xffff0000, v46
	v_lshlrev_b32_e32 v46, 16, v47
	v_and_b32_e32 v47, 0xffff0000, v47
	v_pk_mul_f32 v[46:47], v[0:1], v[46:47] op_sel_hi:[0,1]
	v_pk_mul_f32 v[52:53], v[16:17], v[46:47]
	v_lshlrev_b32_e32 v46, 16, v48
	v_and_b32_e32 v47, 0xffff0000, v48
	v_lshlrev_b32_e32 v48, 16, v49
	v_and_b32_e32 v49, 0xffff0000, v49
	v_pk_mul_f32 v[46:47], v[0:1], v[46:47] op_sel_hi:[0,1]
	v_pk_mul_f32 v[48:49], v[0:1], v[48:49] op_sel_hi:[0,1]
	v_pk_mul_f32 v[46:47], v[10:11], v[46:47]
	v_pk_mul_f32 v[48:49], v[12:13], v[48:49]
	global_store_dwordx4 v[54:55], v[46:49], off offset:16
	v_pk_mul_f32 v[50:51], v[0:1], v[50:51] op_sel_hi:[0,1]
	v_pk_mul_f32 v[50:51], v[14:15], v[50:51]
	v_lshlrev_b32_e32 v46, 16, v42
	v_and_b32_e32 v47, 0xffff0000, v42
	v_lshlrev_b32_e32 v42, 16, v43
	v_and_b32_e32 v43, 0xffff0000, v43
	v_pk_mul_f32 v[42:43], v[0:1], v[42:43] op_sel_hi:[0,1]
	v_pk_mul_f32 v[48:49], v[8:9], v[42:43]
	v_lshlrev_b32_e32 v42, 16, v44
	v_and_b32_e32 v43, 0xffff0000, v44
	v_lshlrev_b32_e32 v44, 16, v45
	v_and_b32_e32 v45, 0xffff0000, v45
	v_pk_mul_f32 v[46:47], v[0:1], v[46:47] op_sel_hi:[0,1]
	v_pk_mul_f32 v[42:43], v[0:1], v[42:43] op_sel_hi:[0,1]
	v_pk_mul_f32 v[44:45], v[0:1], v[44:45] op_sel_hi:[0,1]
	v_pk_mul_f32 v[46:47], v[6:7], v[46:47]
	v_pk_mul_f32 v[42:43], v[2:3], v[42:43]
	v_pk_mul_f32 v[44:45], v[4:5], v[44:45]
	global_store_dwordx4 v[54:55], v[50:53], off
	global_store_dwordx4 v[54:55], v[46:49], off offset:32
	global_store_dwordx4 v[54:55], v[42:45], off offset:48
	s_nop 0
	s_waitcnt vmcnt(26)
	s_waitcnt lgkmcnt(0)
	s_nop 1
	v_add_f32_dpp v0, v106, v106 quad_perm:[1,0,3,2] row_mask:0xf bank_mask:0xf
	s_waitcnt lgkmcnt(0)
	s_nop 1
	v_add_f32_dpp v0, v0, v0 quad_perm:[2,3,0,1] row_mask:0xf bank_mask:0xf
	s_nop 0
	s_waitcnt lgkmcnt(0)
	s_nop 1
	v_add_f32_dpp v0, v0, v0 row_ror:4 row_mask:0xf bank_mask:0xf
	s_nop 0
	s_waitcnt lgkmcnt(0)
; DI float shx(float v, int o) { int l = (int)__builtin_amdgcn_mbcnt_hi(~0u, __builtin_amdgcn_mbcnt_lo(~0u, 0u)); asm volatile("" : "+v"(l)); return __int_as_float(__builtin_amdgcn_ds_bpermute((l ^ o) << 2, __float_as_int(v))); }
; DI void final_norm_phase(const bf16_t* __restrict__ h, const float* __restrict__ ss, float* __restrict__ out, const float* __restrict__ g, int rows) {
;     ...
;     for (int row0 = (blockIdx.x * 8 + wave) * RB; row0 < rows; row0 += gridDim.x * 8 * RB) {
;         u32x4 v[RB][2]; float sp[RB];
; #pragma unroll
;         for (int r = 0; r < RB; ++r) {
;             const bf16_t* hp = h + (size_t)(row0 + r) * D + lane * 16;
;             v[r][0] = *(const u32x4*)hp; v[r][1] = *(const u32x4*)(hp + 8);
;             sp[r] = ss[(size_t)(row0 + r) * 16 + (lane & 15)];
;         }
; #pragma unroll
;         for (int r = 0; r < RB; ++r) {
;             float s = sp[r]; s += shx(s, 1); s += shx(s, 2); s += shx(s, 4); s += shx(s, 8);
;             const float rstd = rsqrtf(s * (1.0f / D) + 1e-6f);
;             float f[16]; unpack8(v[r][0], f); unpack8(v[r][1], f + 8);
;             float* op = out + (size_t)(row0 + r) * D + lane * 16;
; #pragma unroll
;             for (int i = 0; i < 4; ++i) { float4 o; o.x = f[4 * i] * rstd * gg[4 * i]; o.y = f[4 * i + 1] * rstd * gg[4 * i + 1]; o.z = f[4 * i + 2] * rstd * gg[4 * i + 2]; o.w = f[4 * i + 3] * rstd * gg[4 * i + 3]; ((float4*)op)[i] = o; }
;         }
;     }
; }
	s_nop 1
	v_add_f32_dpp v0, v0, v0 row_ror:8 row_mask:0xf bank_mask:0xf
	v_fmamk_f32 v0, v0, 0x3a800000, v194
	v_cmp_gt_f32_e32 vcc, s49, v0
	v_mul_f32_e32 v42, 0x4b800000, v0
	s_nop 0
	v_cndmask_b32_e32 v0, v0, v42, vcc
	v_rsq_f32_e32 v0, v0
	s_nop 0
	v_mul_f32_e32 v42, 0x45800000, v0
	v_cndmask_b32_e32 v0, v0, v42, vcc
	v_lshlrev_b64 v[42:43], 12, v[94:95]
	v_lshl_add_u64 v[46:47], v[88:89], 0, v[42:43]
	v_lshlrev_b32_e32 v42, 16, v38
	v_and_b32_e32 v43, 0xffff0000, v38
	v_lshlrev_b32_e32 v38, 16, v39
	v_and_b32_e32 v39, 0xffff0000, v39
	v_pk_mul_f32 v[38:39], v[0:1], v[38:39] op_sel_hi:[0,1]
	v_pk_mul_f32 v[44:45], v[16:17], v[38:39]
	v_lshlrev_b32_e32 v38, 16, v40
	v_and_b32_e32 v39, 0xffff0000, v40
	v_lshlrev_b32_e32 v40, 16, v41
	v_and_b32_e32 v41, 0xffff0000, v41
	v_pk_mul_f32 v[38:39], v[0:1], v[38:39] op_sel_hi:[0,1]
	v_pk_mul_f32 v[40:41], v[0:1], v[40:41] op_sel_hi:[0,1]
	v_pk_mul_f32 v[38:39], v[10:11], v[38:39]
	v_pk_mul_f32 v[40:41], v[12:13], v[40:41]
	global_store_dwordx4 v[46:47], v[38:41], off offset:16
	v_pk_mul_f32 v[42:43], v[0:1], v[42:43] op_sel_hi:[0,1]
	v_pk_mul_f32 v[42:43], v[14:15], v[42:43]
	v_lshlrev_b32_e32 v38, 16, v34
	v_and_b32_e32 v39, 0xffff0000, v34
	v_lshlrev_b32_e32 v34, 16, v35
	v_and_b32_e32 v35, 0xffff0000, v35
	v_pk_mul_f32 v[34:35], v[0:1], v[34:35] op_sel_hi:[0,1]
	v_pk_mul_f32 v[40:41], v[8:9], v[34:35]
	v_lshlrev_b32_e32 v34, 16, v36
	v_and_b32_e32 v35, 0xffff0000, v36
	v_lshlrev_b32_e32 v36, 16, v37
	v_and_b32_e32 v37, 0xffff0000, v37
	v_pk_mul_f32 v[38:39], v[0:1], v[38:39] op_sel_hi:[0,1]
	v_pk_mul_f32 v[34:35], v[0:1], v[34:35] op_sel_hi:[0,1]
	v_pk_mul_f32 v[36:37], v[0:1], v[36:37] op_sel_hi:[0,1]
	v_pk_mul_f32 v[38:39], v[6:7], v[38:39]
	v_pk_mul_f32 v[34:35], v[2:3], v[34:35]
	v_pk_mul_f32 v[36:37], v[4:5], v[36:37]
	global_store_dwordx4 v[46:47], v[42:45], off
	global_store_dwordx4 v[46:47], v[38:41], off offset:32
	global_store_dwordx4 v[46:47], v[34:37], off offset:48
	s_nop 0
	s_waitcnt vmcnt(27)
	s_waitcnt lgkmcnt(0)
	s_nop 1
	v_add_f32_dpp v0, v105, v105 quad_perm:[1,0,3,2] row_mask:0xf bank_mask:0xf
	s_waitcnt lgkmcnt(0)
	s_nop 1
	v_add_f32_dpp v0, v0, v0 quad_perm:[2,3,0,1] row_mask:0xf bank_mask:0xf
	s_nop 0
	s_waitcnt lgkmcnt(0)
	s_nop 1
	v_add_f32_dpp v0, v0, v0 row_ror:4 row_mask:0xf bank_mask:0xf
	s_nop 0
	s_waitcnt lgkmcnt(0)
	s_nop 1
	v_add_f32_dpp v0, v0, v0 row_ror:8 row_mask:0xf bank_mask:0xf
	v_fmamk_f32 v0, v0, 0x3a800000, v194
	v_cmp_gt_f32_e32 vcc, s49, v0
	v_mul_f32_e32 v34, 0x4b800000, v0
	s_nop 0
	v_cndmask_b32_e32 v0, v0, v34, vcc
	v_rsq_f32_e32 v0, v0
	s_nop 0
	v_mul_f32_e32 v34, 0x45800000, v0
	v_cndmask_b32_e32 v0, v0, v34, vcc
	v_lshlrev_b64 v[34:35], 12, v[92:93]
	v_lshl_add_u64 v[38:39], v[88:89], 0, v[34:35]
	v_lshlrev_b32_e32 v34, 16, v30
	v_and_b32_e32 v35, 0xffff0000, v30
	v_lshlrev_b32_e32 v30, 16, v31
	v_and_b32_e32 v31, 0xffff0000, v31
	v_pk_mul_f32 v[30:31], v[0:1], v[30:31] op_sel_hi:[0,1]
	v_pk_mul_f32 v[36:37], v[16:17], v[30:31]
	v_lshlrev_b32_e32 v30, 16, v32
	v_and_b32_e32 v31, 0xffff0000, v32
	v_lshlrev_b32_e32 v32, 16, v33
	v_and_b32_e32 v33, 0xffff0000, v33
	v_pk_mul_f32 v[30:31], v[0:1], v[30:31] op_sel_hi:[0,1]
	v_pk_mul_f32 v[32:33], v[0:1], v[32:33] op_sel_hi:[0,1]
	v_pk_mul_f32 v[30:31], v[10:11], v[30:31]
	v_pk_mul_f32 v[32:33], v[12:13], v[32:33]
	global_store_dwordx4 v[38:39], v[30:33], off offset:16
	v_pk_mul_f32 v[34:35], v[0:1], v[34:35] op_sel_hi:[0,1]
	v_pk_mul_f32 v[34:35], v[14:15], v[34:35]
	v_lshlrev_b32_e32 v30, 16, v26
	v_and_b32_e32 v31, 0xffff0000, v26
	v_lshlrev_b32_e32 v26, 16, v27
	v_and_b32_e32 v27, 0xffff0000, v27
	v_pk_mul_f32 v[26:27], v[0:1], v[26:27] op_sel_hi:[0,1]
	v_pk_mul_f32 v[32:33], v[8:9], v[26:27]
	v_lshlrev_b32_e32 v26, 16, v28
	v_and_b32_e32 v27, 0xffff0000, v28
	v_lshlrev_b32_e32 v28, 16, v29
	v_and_b32_e32 v29, 0xffff0000, v29
	v_pk_mul_f32 v[30:31], v[0:1], v[30:31] op_sel_hi:[0,1]
	v_pk_mul_f32 v[26:27], v[0:1], v[26:27] op_sel_hi:[0,1]
	v_pk_mul_f32 v[28:29], v[0:1], v[28:29] op_sel_hi:[0,1]
	v_pk_mul_f32 v[30:31], v[6:7], v[30:31]
	v_pk_mul_f32 v[26:27], v[2:3], v[26:27]
	v_pk_mul_f32 v[28:29], v[4:5], v[28:29]
	global_store_dwordx4 v[38:39], v[34:37], off
	global_store_dwordx4 v[38:39], v[30:33], off offset:32
	global_store_dwordx4 v[38:39], v[26:29], off offset:48
	s_nop 0
	s_waitcnt vmcnt(28)
	s_waitcnt lgkmcnt(0)
	s_nop 1
	v_add_f32_dpp v0, v104, v104 quad_perm:[1,0,3,2] row_mask:0xf bank_mask:0xf
	s_waitcnt lgkmcnt(0)
	s_nop 1
	v_add_f32_dpp v0, v0, v0 quad_perm:[2,3,0,1] row_mask:0xf bank_mask:0xf
	s_nop 0
	s_waitcnt lgkmcnt(0)
	s_nop 1
	v_add_f32_dpp v0, v0, v0 row_ror:4 row_mask:0xf bank_mask:0xf
	s_nop 0
	s_waitcnt lgkmcnt(0)
	s_nop 1
	v_add_f32_dpp v0, v0, v0 row_ror:8 row_mask:0xf bank_mask:0xf
	v_fmamk_f32 v0, v0, 0x3a800000, v194
	v_cmp_gt_f32_e32 vcc, s49, v0
	v_mul_f32_e32 v26, 0x4b800000, v0
	s_nop 0
	v_cndmask_b32_e32 v0, v0, v26, vcc
	v_rsq_f32_e32 v0, v0
	s_nop 0
	v_mul_f32_e32 v26, 0x45800000, v0
	v_cndmask_b32_e32 v0, v0, v26, vcc
	v_lshlrev_b64 v[26:27], 12, v[90:91]
	v_lshl_add_u64 v[30:31], v[88:89], 0, v[26:27]
	v_lshlrev_b32_e32 v26, 16, v22
	v_and_b32_e32 v27, 0xffff0000, v22
	v_lshlrev_b32_e32 v22, 16, v23
	v_and_b32_e32 v23, 0xffff0000, v23
	v_pk_mul_f32 v[22:23], v[0:1], v[22:23] op_sel_hi:[0,1]
	v_pk_mul_f32 v[28:29], v[16:17], v[22:23]
	v_lshlrev_b32_e32 v22, 16, v24
	v_and_b32_e32 v23, 0xffff0000, v24
	v_lshlrev_b32_e32 v24, 16, v25
	v_and_b32_e32 v25, 0xffff0000, v25
	v_pk_mul_f32 v[22:23], v[0:1], v[22:23] op_sel_hi:[0,1]
	v_pk_mul_f32 v[24:25], v[0:1], v[24:25] op_sel_hi:[0,1]
	v_pk_mul_f32 v[22:23], v[10:11], v[22:23]
	v_pk_mul_f32 v[24:25], v[12:13], v[24:25]
	global_store_dwordx4 v[30:31], v[22:25], off offset:16
	v_pk_mul_f32 v[26:27], v[0:1], v[26:27] op_sel_hi:[0,1]
	v_cmp_le_i32_e32 vcc, s36, v82
	v_lshlrev_b32_e32 v22, 16, v18
	v_and_b32_e32 v23, 0xffff0000, v18
	v_lshlrev_b32_e32 v18, 16, v19
	v_and_b32_e32 v19, 0xffff0000, v19
	v_pk_mul_f32 v[18:19], v[0:1], v[18:19] op_sel_hi:[0,1]
	v_pk_mul_f32 v[24:25], v[8:9], v[18:19]
	v_lshlrev_b32_e32 v18, 16, v20
	v_and_b32_e32 v19, 0xffff0000, v20
	v_lshlrev_b32_e32 v20, 16, v21
	v_and_b32_e32 v21, 0xffff0000, v21
	v_pk_mul_f32 v[22:23], v[0:1], v[22:23] op_sel_hi:[0,1]
	v_pk_mul_f32 v[18:19], v[0:1], v[18:19] op_sel_hi:[0,1]
	v_pk_mul_f32 v[20:21], v[0:1], v[20:21] op_sel_hi:[0,1]
	v_pk_mul_f32 v[26:27], v[14:15], v[26:27]
	v_pk_mul_f32 v[22:23], v[6:7], v[22:23]
	v_pk_mul_f32 v[18:19], v[2:3], v[18:19]
	v_pk_mul_f32 v[20:21], v[4:5], v[20:21]
	s_or_b64 s[4:5], vcc, s[4:5]
	global_store_dwordx4 v[30:31], v[26:29], off
	global_store_dwordx4 v[30:31], v[22:25], off offset:32
	global_store_dwordx4 v[30:31], v[18:21], off offset:48
	s_andn2_b64 exec, exec, s[4:5]
	s_cbranch_execnz .LBB0_1388
	s_getpc_b64 s[98:99]
